# g8 plus k_r data loads of phase_odd_rows (lanes 0-1) issued at the row top into spare registers
# baseline (speedup 1.0000x reference)
; __device__ __forceinline__ unsigned pk2(float lo, float hi) { unsigned r; asm("v_cvt_pk_bf16_f32 %0, %1, %2" : "=v"(r) : "v"(lo), "v"(hi)); return r; }
; __device__ __forceinline__ float bflo(unsigned u) { return __uint_as_float(u << 16); }
; __device__ __forceinline__ float bfhi(unsigned u) { return __uint_as_float(u & 0xffff0000u); }
; __device__ __forceinline__ void phase_odd_rows(const Params& p, int o, int grp) {
;     ...
;         {
;             u32x4 v = {0u, 0u, 0u, 0u}; if (lane < 48) v = *(const u32x4*)(ur + 2048 + lane * 8);
;             float x[8] = {bflo(v.x), bfhi(v.x), bflo(v.y), bfhi(v.y), bflo(v.z), bfhi(v.z), bflo(v.w), bfhi(v.w)};
;             float ss = 0.f;
; #pragma unroll
;             for (int j = 0; j < 8; ++j) ss += x[j] * x[j];
;             const float r = rsqrtf(wave_sum(ss) * (1.f / 384.f) + EPS);
;             if (lane < 48) { u32x4 ov; ov.x = pk2(x[0] * r * gqa[0], x[1] * r * gqa[1]); ov.y = pk2(x[2] * r * gqa[2], x[3] * r * gqa[3]); ov.z = pk2(x[4] * r * gqb[0], x[5] * r * gqb[1]); ov.w = pk2(x[6] * r * gqb[2], x[7] * r * gqb[3]);
;                 *(u32x4*)(ur + 2048 + lane * 8) = ov; }
;         }
;     ...
;         if (lane < 2) {
;             const int ax = lane;
;             const u32x4 a = *(const u32x4*)(ur + 2688 + 16 * ax), bq = *(const u32x4*)(ur + 2688 + 16 * ax + 8);
.LBB0_571:
	s_or_b64 exec, exec, s[12:13]
	v_mov_b32_e32 v68, 0
	v_mov_b32_e32 v69, 0
	v_mov_b32_e32 v70, 0
	v_mov_b32_e32 v71, 0
	s_and_saveexec_b64 s[12:13], s[4:5]
	v_add_co_u32_e32 v72, vcc, 0x13ad9000, v20
	s_nop 1
	v_addc_co_u32_e32 v73, vcc, 0, v21, vcc
	global_load_dwordx4 v[68:71], v[72:73], off offset:2560
	s_or_b64 exec, exec, s[12:13]
	v_lshl_add_u64 v[86:87], v[26:27], 0, s[16:17]
	v_add_co_u32_e32 v86, vcc, 0x13ad8000, v86
	s_nop 1
	v_addc_co_u32_e32 v87, vcc, 0, v87, vcc
	global_load_dwordx4 v[96:99], v[86:87], off offset:3840
	global_load_dwordx4 v[100:103], v[86:87], off offset:3872
	s_and_saveexec_b64 s[12:13], s[8:9]
	v_lshl_add_u64 v[88:89], v[24:25], 0, s[16:17]
	s_mov_b64 s[14:15], 0x13ad9c00
	v_lshl_add_u64 v[90:91], v[88:89], 0, s[14:15]
	v_add_co_u32_e32 v88, vcc, 0x13ad9000, v88
	s_nop 1
	v_addc_co_u32_e32 v89, vcc, 0, v89, vcc
	global_load_dwordx4 v[104:107], v[88:89], off offset:3072
	global_load_dwordx4 v[108:111], v[90:91], off offset:16
	s_or_b64 exec, exec, s[12:13]
	s_waitcnt vmcnt(5)
	v_and_b32_e32 v33, 0xffff0000, v16
	v_lshlrev_b32_e32 v42, 16, v16
	v_lshlrev_b32_e32 v32, 16, v17
	v_and_b32_e32 v23, 0xffff0000, v17
	v_lshlrev_b32_e32 v17, 16, v19
	v_and_b32_e32 v16, 0xffff0000, v19
	v_mul_f32_e32 v19, v33, v33
	v_fmac_f32_e32 v19, v42, v42
	v_fmac_f32_e32 v19, v32, v32
	v_lshlrev_b32_e32 v22, 16, v18
	v_fmac_f32_e32 v19, v23, v23
	v_and_b32_e32 v18, 0xffff0000, v18
	v_fmac_f32_e32 v19, v22, v22
	v_fmac_f32_e32 v19, v18, v18
	v_fmac_f32_e32 v19, v17, v17
	v_fmac_f32_e32 v19, v16, v16
	ds_bpermute_b32 v43, v35, v19
	s_waitcnt lgkmcnt(0)
	v_add_f32_e32 v19, v19, v43
	ds_bpermute_b32 v43, v36, v19
	s_waitcnt lgkmcnt(0)
	v_add_f32_e32 v19, v19, v43
	ds_bpermute_b32 v43, v37, v19
	s_waitcnt lgkmcnt(0)
	v_add_f32_e32 v19, v19, v43
	ds_bpermute_b32 v43, v38, v19
	s_waitcnt lgkmcnt(0)
	v_add_f32_e32 v19, v19, v43
	ds_bpermute_b32 v43, v39, v19
	s_waitcnt lgkmcnt(0)
	v_add_f32_e32 v19, v19, v43
	ds_bpermute_b32 v43, v40, v19
	s_and_saveexec_b64 s[12:13], s[0:1]
	s_cbranch_execz .LBB0_573
	s_waitcnt lgkmcnt(0)
	v_add_f32_e32 v19, v19, v43
	v_fmamk_f32 v19, v19, 0x3b2aaaab, v195
	v_mul_f32_e32 v43, 0x4b800000, v19
	v_cmp_gt_f32_e32 vcc, s41, v19
	s_nop 1
	v_cndmask_b32_e32 v19, v19, v43, vcc
	v_rsq_f32_e32 v19, v19
	s_nop 0
	v_mul_f32_e32 v43, 0x45800000, v19
	v_cndmask_b32_e32 v19, v19, v43, vcc
	v_mul_f32_e32 v16, v19, v16
	v_mul_f32_e32 v17, v19, v17
	v_mul_f32_e32 v16, v11, v16
	v_mul_f32_e32 v42, v19, v42
	v_mul_f32_e32 v17, v10, v17
	v_cvt_pk_bf16_f32 v45, v17, v16
	v_add_co_u32_e32 v16, vcc, 0x13ad9000, v20
	v_mul_f32_e32 v33, v19, v33
	v_mul_f32_e32 v42, v4, v42
	v_mul_f32_e32 v32, v19, v32
	v_mul_f32_e32 v23, v19, v23
	v_mul_f32_e32 v22, v19, v22
	v_mul_f32_e32 v18, v19, v18
	v_addc_co_u32_e32 v17, vcc, 0, v21, vcc
	v_mul_f32_e32 v33, v5, v33
	v_cvt_pk_bf16_f32 v42, v42, v33
	v_mul_f32_e32 v32, v6, v32
	v_mul_f32_e32 v23, v7, v23
	v_cvt_pk_bf16_f32 v43, v32, v23
	v_mul_f32_e32 v22, v8, v22
	v_mul_f32_e32 v18, v9, v18
	v_cvt_pk_bf16_f32 v44, v22, v18
	global_store_dwordx4 v[16:17], v[42:45], off offset:1792

; __device__ __forceinline__ unsigned pk2(float lo, float hi) { unsigned r; asm("v_cvt_pk_bf16_f32 %0, %1, %2" : "=v"(r) : "v"(lo), "v"(hi)); return r; }
; __device__ __forceinline__ float bflo(unsigned u) { return __uint_as_float(u << 16); }
; __device__ __forceinline__ float bfhi(unsigned u) { return __uint_as_float(u & 0xffff0000u); }
; __device__ __forceinline__ void phase_odd_rows(const Params& p, int o, int grp) {
;     ...
;         if (lane < 2) {
;             const int ax = lane;
;             const u32x4 a = *(const u32x4*)(ur + 2688 + 16 * ax), bq = *(const u32x4*)(ur + 2688 + 16 * ax + 8);
;             u32x4 oa = a, ob = bq;
;             if (lat) {
;                 const float* tp = rt + ((ax ? pcol : prow) * 16) * 2;
; #pragma unroll
;                 for (int q = 0; q < 4; ++q) {
;                     const f32x4 c0 = *(const f32x4*)(tp + 8 * q), c1 = *(const f32x4*)(tp + 8 * q + 4);
;                     const float x1a = bflo(a[q]), x1b = bfhi(a[q]), x2a = bflo(bq[q]), x2b = bfhi(bq[q]);
;                     oa[q] = pk2(x1a * c0[0] - x2a * c0[1], x1b * c1[0] - x2b * c1[1]);
;                     ob[q] = pk2(x2a * c0[0] + x1a * c0[1], x2b * c1[0] + x1b * c1[1]);
;                 }
;             }
; #pragma unroll
;             for (int h = 0; h < 8; ++h) { bf16_t* kp = KM + (size_t)lr * 768 + h * 96 + 64 + 16 * ax; *(u32x4*)kp = oa; *(u32x4*)(kp + 8) = ob; }
.LBB0_579:
	s_or_b64 exec, exec, s[34:35]
	s_and_saveexec_b64 s[34:35], s[8:9]
	s_cbranch_execz .LBB0_568
	v_mov_b64_e32 v[16:17], v[104:105]
	v_mov_b64_e32 v[18:19], v[106:107]
	v_mov_b64_e32 v[20:21], v[108:109]
	v_mov_b64_e32 v[22:23], v[110:111]
	s_and_saveexec_b64 s[14:15], s[12:13]
	s_xor_b64 s[12:13], exec, s[14:15]
	s_andn2_saveexec_b64 s[12:13], s[12:13]
	s_cbranch_execz .LBB0_567
	v_cndmask_b32_e64 v32, v42, v43, s[10:11]
	v_lshlrev_b32_e32 v32, 5, v32
	v_ashrrev_i32_e32 v33, 31, v32
	v_lshl_add_u64 v[32:33], v[32:33], 2, s[64:65]
	global_load_dwordx2 v[42:43], v[32:33], off
	global_load_dwordx2 v[44:45], v[32:33], off offset:16
	global_load_dwordx2 v[74:75], v[32:33], off offset:32
	global_load_dwordx2 v[76:77], v[32:33], off offset:48
	global_load_dwordx2 v[78:79], v[32:33], off offset:64
	global_load_dwordx2 v[80:81], v[32:33], off offset:80
	global_load_dwordx2 v[82:83], v[32:33], off offset:96
	global_load_dwordx2 v[84:85], v[32:33], off offset:112
	v_lshlrev_b32_e32 v47, 16, v16
	v_lshlrev_b32_e32 v46, 16, v20
	s_waitcnt vmcnt(7)
	v_pk_mul_f32 v[48:49], v[42:43], v[46:47] op_sel:[0,1] op_sel_hi:[1,0]
	v_pk_mul_f32 v[42:43], v[42:43], v[46:47]
	v_sub_f32_e32 v48, v48, v49
	v_add_f32_e32 v49, v42, v43
	v_and_b32_e32 v43, 0xffff0000, v16
	v_and_b32_e32 v42, 0xffff0000, v20
	s_waitcnt vmcnt(6)
	v_pk_mul_f32 v[46:47], v[44:45], v[42:43] op_sel:[0,1] op_sel_hi:[1,0]
	v_pk_mul_f32 v[42:43], v[44:45], v[42:43]
	v_sub_f32_e32 v16, v46, v47
	v_add_f32_e32 v20, v42, v43
	v_lshlrev_b32_e32 v47, 16, v17
	v_lshlrev_b32_e32 v46, 16, v21
	v_cvt_pk_bf16_f32 v16, v48, v16
	v_cvt_pk_bf16_f32 v20, v49, v20
	s_waitcnt vmcnt(5)
	v_mov_b64_e32 v[42:43], v[74:75]
	v_pk_mul_f32 v[48:49], v[42:43], v[46:47] op_sel:[0,1] op_sel_hi:[1,0]
	v_pk_mul_f32 v[42:43], v[42:43], v[46:47]
	v_sub_f32_e32 v48, v48, v49
	v_add_f32_e32 v49, v42, v43
	v_and_b32_e32 v43, 0xffff0000, v17
	v_and_b32_e32 v42, 0xffff0000, v21
	s_waitcnt vmcnt(4)
	v_mov_b64_e32 v[44:45], v[76:77]
	v_pk_mul_f32 v[46:47], v[44:45], v[42:43] op_sel:[0,1] op_sel_hi:[1,0]
	v_pk_mul_f32 v[42:43], v[44:45], v[42:43]
	v_sub_f32_e32 v17, v46, v47
	v_add_f32_e32 v21, v42, v43
	v_lshlrev_b32_e32 v47, 16, v18
	v_lshlrev_b32_e32 v46, 16, v22
	v_cvt_pk_bf16_f32 v17, v48, v17
	v_cvt_pk_bf16_f32 v21, v49, v21
	s_waitcnt vmcnt(3)
	v_mov_b64_e32 v[42:43], v[78:79]
	v_pk_mul_f32 v[48:49], v[42:43], v[46:47] op_sel:[0,1] op_sel_hi:[1,0]
	v_pk_mul_f32 v[42:43], v[42:43], v[46:47]
	v_sub_f32_e32 v48, v48, v49
	v_add_f32_e32 v49, v42, v43
	v_and_b32_e32 v43, 0xffff0000, v18
	v_and_b32_e32 v42, 0xffff0000, v22
	s_waitcnt vmcnt(2)
	v_mov_b64_e32 v[44:45], v[80:81]
	v_pk_mul_f32 v[46:47], v[44:45], v[42:43] op_sel:[0,1] op_sel_hi:[1,0]
	v_pk_mul_f32 v[42:43], v[44:45], v[42:43]
	v_lshlrev_b32_e32 v45, 16, v23
	v_add_f32_e32 v22, v42, v43
	s_nop 0
	v_lshlrev_b32_e32 v44, 16, v19
	v_sub_f32_e32 v18, v46, v47
	v_cvt_pk_bf16_f32 v18, v48, v18
	v_cvt_pk_bf16_f32 v22, v49, v22
	s_waitcnt vmcnt(1)
	v_mov_b64_e32 v[42:43], v[82:83]
	v_pk_mul_f32 v[46:47], v[42:43], v[44:45]
	s_nop 0
	v_sub_f32_e32 v50, v46, v47
	v_and_b32_e32 v47, 0xffff0000, v23
	v_and_b32_e32 v46, 0xffff0000, v19
	s_waitcnt vmcnt(0)
	v_mov_b64_e32 v[32:33], v[84:85]
	v_pk_mul_f32 v[48:49], v[32:33], v[46:47]
	v_pk_mul_f32 v[42:43], v[42:43], v[44:45] op_sel:[0,1] op_sel_hi:[1,0]
	v_sub_f32_e32 v19, v48, v49
	v_add_f32_e32 v23, v42, v43
	v_pk_mul_f32 v[32:33], v[32:33], v[46:47] op_sel:[0,1] op_sel_hi:[1,0]
	v_cvt_pk_bf16_f32 v19, v50, v19
	s_nop 0
	v_add_f32_e32 v32, v32, v33
	v_cvt_pk_bf16_f32 v23, v23, v32
	s_branch .LBB0_567
